# v119 plus nt on LRU pass-1 output-stream stores
# baseline (speedup 1.0000x reference)
; __device__ __forceinline__ float sigm(float x) { return __builtin_amdgcn_rcpf(1.f + __expf(-x)); }
; #define LAS __attribute__((address_space(3)))
; template <int PASS>
; __device__ __forceinline__ void lru_unit(const LruPtrs& args, LAS unsigned char* lds, int chunk, int bl, int g, int ck) {
;     ...
; #pragma unroll
;         for (int q = 0; q < 8; ++q) {
;             const f32x4 br = *(const LAS f32x4*)(PRM + 5 * 64 + 8 * q + 4 * hi), bi = *(const LAS f32x4*)(PRM + 6 * 64 + 8 * q + 4 * hi), cf = *(const LAS f32x4*)(PRM + 7 * 64 + 8 * q + 4 * hi);
; #pragma unroll
;             for (int p = 0; p < 4; ++p) { const int rb = q >> 2, r = (q & 3) * 4 + p;
;                 const float rr = pg8::sigm(ar[rb][r] + br[p]), ii = pg8::sigm(ai_[rb][r] + bi[p]);
;                 const float a0 = __builtin_amdgcn_exp2f(cf[p] * rr);
;                 av[q][p] = a0; uv[q][p] = __builtin_amdgcn_sqrtf(fmaxf(1.f - a0 * a0, 0.f)) * (ii * xc[q][p]); }
;         }
.Llpf_skip:
	v_exp_f32_e32 v40, v40
	v_add_f32_e32 v0, 1.0, v39
	v_fma_f32 v39, -v38, v38, 1.0
	v_rcp_f32_e32 v0, v0
	v_max_f32_e32 v39, 0, v39
	v_add_f32_e32 v40, 1.0, v40
	s_waitcnt lgkmcnt(1)
	v_add_f32_e32 v42, v42, v78
	v_sqrt_f32_e32 v39, v39
	v_rcp_f32_e32 v40, v40
	v_mul_f32_e32 v42, 0xbfb8aa3b, v42
	v_exp_f32_e32 v42, v42
	v_mul_f32_e32 v0, v109, v0
	v_add_f32_e32 v41, v57, v139
	v_mul_f32_e32 v41, 0xbfb8aa3b, v41
	v_mul_f32_e32 v39, v0, v39
	v_mul_f32_e32 v0, v143, v40
	v_exp_f32_e32 v41, v41
	v_exp_f32_e32 v40, v0
	ds_read_b128 v[114:117], v89 offset:13888
	ds_read_b128 v[118:121], v89 offset:14144
	v_add_f32_e32 v42, 1.0, v42
	v_add_f32_e32 v43, v43, v79
	v_rcp_f32_e32 v42, v42
	v_mul_f32_e32 v43, 0xbfb8aa3b, v43
	v_exp_f32_e32 v43, v43
	v_add_f32_e32 v0, 1.0, v41
	v_fma_f32 v41, -v40, v40, 1.0
	s_waitcnt lgkmcnt(1)
	v_add_f32_e32 v54, v58, v114
	v_rcp_f32_e32 v0, v0
	v_max_f32_e32 v41, 0, v41
	v_mul_f32_e32 v54, 0xbfb8aa3b, v54
	s_waitcnt lgkmcnt(0)
	v_mul_f32_e32 v42, v118, v42
	v_sqrt_f32_e32 v41, v41
	v_exp_f32_e32 v55, v54
	v_exp_f32_e32 v54, v42
	v_add_f32_e32 v43, 1.0, v43
	v_rcp_f32_e32 v43, v43
	v_mul_f32_e32 v0, v100, v0
	v_mul_f32_e32 v41, v0, v41
	v_add_f32_e32 v0, 1.0, v55
	v_fma_f32 v42, -v54, v54, 1.0
	v_add_f32_e32 v55, v59, v115
	v_rcp_f32_e32 v0, v0
	v_max_f32_e32 v42, 0, v42
	v_mul_f32_e32 v55, 0xbfb8aa3b, v55
	v_mul_f32_e32 v43, v119, v43
	v_sqrt_f32_e32 v42, v42
	v_exp_f32_e32 v57, v55
	v_exp_f32_e32 v56, v43
	v_mul_f32_e32 v0, v106, v0
	v_mul_f32_e32 v55, v0, v42
	v_add_f32_e32 v0, 1.0, v57
	v_fma_f32 v42, -v56, v56, 1.0
	v_add_f32_e32 v43, v44, v80
	v_rcp_f32_e32 v0, v0
	v_mul_f32_e32 v43, 0xbfb8aa3b, v43
	v_max_f32_e32 v42, 0, v42
	v_exp_f32_e32 v43, v43
	v_sqrt_f32_e32 v44, v42
	v_mul_f32_e32 v0, v103, v0
	v_add_f32_e32 v46, v46, v110
	v_add_f32_e32 v42, 1.0, v43
	v_mul_f32_e32 v57, v0, v44
	v_add_f32_e32 v44, v45, v81
	v_rcp_f32_e32 v42, v42
	v_mul_f32_e32 v44, 0xbfb8aa3b, v44
	v_exp_f32_e32 v44, v44
	v_add_f32_e32 v43, v60, v116
	v_mul_f32_e32 v43, 0xbfb8aa3b, v43
	v_mul_f32_e32 v42, v120, v42
	v_exp_f32_e32 v43, v43
	v_exp_f32_e32 v42, v42
	v_add_f32_e32 v44, 1.0, v44
	v_rcp_f32_e32 v44, v44
	v_mul_f32_e32 v46, 0xbfb8aa3b, v46
	v_exp_f32_e32 v46, v46
	v_add_f32_e32 v0, 1.0, v43
	v_fma_f32 v43, -v42, v42, 1.0
	v_add_f32_e32 v45, v61, v117
	ds_read_b128 v[122:125], v89 offset:13920
	ds_read_b128 v[126:129], v89 offset:14176
	v_rcp_f32_e32 v0, v0
	v_max_f32_e32 v43, 0, v43
	v_mul_f32_e32 v45, 0xbfb8aa3b, v45
	v_mul_f32_e32 v44, v121, v44
	v_sqrt_f32_e32 v43, v43
	v_exp_f32_e32 v45, v45
	v_exp_f32_e32 v44, v44
	v_add_f32_e32 v46, 1.0, v46
	v_add_f32_e32 v47, v47, v111
	v_rcp_f32_e32 v46, v46
	v_mul_f32_e32 v47, 0xbfb8aa3b, v47
	v_exp_f32_e32 v47, v47
	v_mul_f32_e32 v0, v102, v0
	v_mul_f32_e32 v43, v0, v43
	v_add_f32_e32 v0, 1.0, v45
	v_fma_f32 v45, -v44, v44, 1.0
	s_waitcnt lgkmcnt(1)
	v_add_f32_e32 v58, v62, v122
	v_rcp_f32_e32 v0, v0
	v_max_f32_e32 v45, 0, v45
	v_mul_f32_e32 v58, 0xbfb8aa3b, v58
	s_waitcnt lgkmcnt(0)
	v_mul_f32_e32 v46, v126, v46
	v_sqrt_f32_e32 v45, v45
	v_exp_f32_e32 v59, v58
	v_exp_f32_e32 v58, v46
	v_add_f32_e32 v47, 1.0, v47
	v_rcp_f32_e32 v47, v47
	v_mul_f32_e32 v0, v99, v0
	v_mul_f32_e32 v45, v0, v45
	v_add_f32_e32 v0, 1.0, v59
	v_fma_f32 v46, -v58, v58, 1.0
	v_rcp_f32_e32 v0, v0
	v_max_f32_e32 v46, 0, v46
	v_add_f32_e32 v59, v63, v123
	v_mul_f32_e32 v47, v127, v47
	v_sqrt_f32_e32 v46, v46
	v_mul_f32_e32 v59, 0xbfb8aa3b, v59
	v_exp_f32_e32 v60, v47
	v_add_f32_e32 v47, v48, v112
	v_exp_f32_e32 v61, v59
	v_mul_f32_e32 v47, 0xbfb8aa3b, v47
	v_exp_f32_e32 v47, v47
	v_mul_f32_e32 v0, v97, v0
	v_mul_f32_e32 v59, v0, v46
	v_fma_f32 v46, -v60, v60, 1.0
	v_add_f32_e32 v0, 1.0, v61
	v_max_f32_e32 v46, 0, v46
	v_rcp_f32_e32 v0, v0
	v_sqrt_f32_e32 v48, v46
	v_add_f32_e32 v46, 1.0, v47
	v_rcp_f32_e32 v46, v46
	v_mul_f32_e32 v0, v96, v0
	v_add_f32_e32 v47, v64, v124
	v_mul_f32_e32 v47, 0xbfb8aa3b, v47
	v_mul_f32_e32 v46, v128, v46
	v_mul_f32_e32 v61, v0, v48
	v_add_f32_e32 v48, v49, v113
	v_exp_f32_e32 v47, v47
	v_exp_f32_e32 v46, v46
	v_mul_f32_e32 v48, 0xbfb8aa3b, v48
	ds_read_b128 v[78:81], v89 offset:13696
	ds_read_b128 v[110:113], v89 offset:13728
	v_exp_f32_e32 v48, v48
	v_add_f32_e32 v0, 1.0, v47
	v_fma_f32 v47, -v46, v46, 1.0
	v_rcp_f32_e32 v0, v0
	v_max_f32_e32 v47, 0, v47
	v_add_f32_e32 v48, 1.0, v48
	s_waitcnt lgkmcnt(1)
	v_add_f32_e32 v2, v2, v78
	v_sqrt_f32_e32 v47, v47
	v_rcp_f32_e32 v48, v48
	v_mul_f32_e32 v2, 0xbfb8aa3b, v2
	v_exp_f32_e32 v2, v2
	v_mul_f32_e32 v0, v95, v0
	v_add_f32_e32 v49, v65, v125
	v_mul_f32_e32 v49, 0xbfb8aa3b, v49
	v_mul_f32_e32 v47, v0, v47
	v_mul_f32_e32 v0, v129, v48
	v_exp_f32_e32 v49, v49
	v_exp_f32_e32 v48, v0
	ds_read_b128 v[114:117], v89 offset:13952
	ds_read_b128 v[118:121], v89 offset:14208
	v_add_f32_e32 v2, 1.0, v2
	v_add_f32_e32 v3, v3, v79
	v_rcp_f32_e32 v2, v2
	v_mul_f32_e32 v3, 0xbfb8aa3b, v3
	v_exp_f32_e32 v3, v3
	v_add_f32_e32 v0, 1.0, v49
	v_fma_f32 v49, -v48, v48, 1.0
	s_waitcnt lgkmcnt(1)
	v_add_f32_e32 v18, v18, v114
	v_rcp_f32_e32 v0, v0
	v_max_f32_e32 v49, 0, v49
	v_mul_f32_e32 v18, 0xbfb8aa3b, v18
	s_waitcnt lgkmcnt(0)
; __device__ __forceinline__ float sigm(float x) { return __builtin_amdgcn_rcpf(1.f + __expf(-x)); }
; #define LAS __attribute__((address_space(3)))
; template <int PASS>
; __device__ __forceinline__ void lru_unit(const LruPtrs& args, LAS unsigned char* lds, int chunk, int bl, int g, int ck) {
;     ...
; #pragma unroll
;         for (int q = 0; q < 8; ++q) {
;             const f32x4 br = *(const LAS f32x4*)(PRM + 5 * 64 + 8 * q + 4 * hi), bi = *(const LAS f32x4*)(PRM + 6 * 64 + 8 * q + 4 * hi), cf = *(const LAS f32x4*)(PRM + 7 * 64 + 8 * q + 4 * hi);
; #pragma unroll
;             for (int p = 0; p < 4; ++p) { const int rb = q >> 2, r = (q & 3) * 4 + p;
;                 const float rr = pg8::sigm(ar[rb][r] + br[p]), ii = pg8::sigm(ai_[rb][r] + bi[p]);
;                 const float a0 = __builtin_amdgcn_exp2f(cf[p] * rr);
;                 av[q][p] = a0; uv[q][p] = __builtin_amdgcn_sqrtf(fmaxf(1.f - a0 * a0, 0.f)) * (ii * xc[q][p]); }
;         }
	v_mul_f32_e32 v2, v118, v2
	v_sqrt_f32_e32 v49, v49
	v_exp_f32_e32 v18, v18
	v_exp_f32_e32 v62, v2
	v_add_f32_e32 v3, 1.0, v3
	v_rcp_f32_e32 v3, v3
	v_mul_f32_e32 v0, v90, v0
	v_mul_f32_e32 v49, v0, v49
	v_add_f32_e32 v0, 1.0, v18
	v_fma_f32 v2, -v62, v62, 1.0
	v_add_f32_e32 v18, v19, v115
	v_rcp_f32_e32 v0, v0
	v_max_f32_e32 v2, 0, v2
	v_mul_f32_e32 v18, 0xbfb8aa3b, v18
	v_mul_f32_e32 v3, v119, v3
	v_sqrt_f32_e32 v2, v2
	v_exp_f32_e32 v18, v18
	v_exp_f32_e32 v64, v3
	v_mul_f32_e32 v0, v91, v0
	v_mul_f32_e32 v63, v0, v2
	v_add_f32_e32 v0, 1.0, v18
	v_fma_f32 v2, -v64, v64, 1.0
	v_add_f32_e32 v3, v4, v80
	v_rcp_f32_e32 v0, v0
	v_mul_f32_e32 v3, 0xbfb8aa3b, v3
	v_max_f32_e32 v2, 0, v2
	v_exp_f32_e32 v3, v3
	v_sqrt_f32_e32 v4, v2
	v_mul_f32_e32 v0, v107, v0
	v_add_f32_e32 v6, v6, v110
	v_add_f32_e32 v2, 1.0, v3
	v_mul_f32_e32 v65, v0, v4
	v_add_f32_e32 v4, v5, v81
	v_rcp_f32_e32 v2, v2
	v_mul_f32_e32 v4, 0xbfb8aa3b, v4
	v_exp_f32_e32 v4, v4
	v_add_f32_e32 v3, v20, v116
	v_mul_f32_e32 v3, 0xbfb8aa3b, v3
	v_mul_f32_e32 v2, v120, v2
	v_exp_f32_e32 v3, v3
	v_exp_f32_e32 v2, v2
	v_add_f32_e32 v4, 1.0, v4
	v_rcp_f32_e32 v4, v4
	v_mul_f32_e32 v6, 0xbfb8aa3b, v6
	v_exp_f32_e32 v6, v6
	v_add_f32_e32 v0, 1.0, v3
	v_fma_f32 v3, -v2, v2, 1.0
	v_add_f32_e32 v5, v21, v117
	ds_read_b128 v[122:125], v89 offset:13984
	ds_read_b128 v[126:129], v89 offset:14240
	v_rcp_f32_e32 v0, v0
	v_max_f32_e32 v3, 0, v3
	v_mul_f32_e32 v5, 0xbfb8aa3b, v5
	v_mul_f32_e32 v4, v121, v4
	v_sqrt_f32_e32 v3, v3
	v_exp_f32_e32 v5, v5
	v_exp_f32_e32 v4, v4
	v_add_f32_e32 v6, 1.0, v6
	v_add_f32_e32 v7, v7, v111
	v_rcp_f32_e32 v6, v6
	v_mul_f32_e32 v7, 0xbfb8aa3b, v7
	v_exp_f32_e32 v7, v7
	v_mul_f32_e32 v0, v108, v0
	v_mul_f32_e32 v3, v0, v3
	v_add_f32_e32 v0, 1.0, v5
	v_fma_f32 v5, -v4, v4, 1.0
	s_waitcnt lgkmcnt(1)
	v_add_f32_e32 v18, v22, v122
	v_rcp_f32_e32 v0, v0
	v_max_f32_e32 v5, 0, v5
	v_mul_f32_e32 v18, 0xbfb8aa3b, v18
	s_waitcnt lgkmcnt(0)
	v_mul_f32_e32 v6, v126, v6
	v_sqrt_f32_e32 v5, v5
	v_exp_f32_e32 v19, v18
	v_exp_f32_e32 v18, v6
	v_add_f32_e32 v7, 1.0, v7
	v_rcp_f32_e32 v7, v7
	v_mul_f32_e32 v0, v105, v0
	v_mul_f32_e32 v5, v0, v5
	v_add_f32_e32 v0, 1.0, v19
	v_fma_f32 v6, -v18, v18, 1.0
	v_rcp_f32_e32 v0, v0
	v_max_f32_e32 v6, 0, v6
	v_add_f32_e32 v19, v23, v123
	v_mul_f32_e32 v7, v127, v7
	v_sqrt_f32_e32 v6, v6
	v_mul_f32_e32 v19, 0xbfb8aa3b, v19
	v_exp_f32_e32 v20, v7
	v_add_f32_e32 v7, v8, v112
	v_exp_f32_e32 v21, v19
	v_mul_f32_e32 v7, 0xbfb8aa3b, v7
	v_exp_f32_e32 v7, v7
	v_mul_f32_e32 v0, v104, v0
	v_mul_f32_e32 v19, v0, v6
	v_fma_f32 v6, -v20, v20, 1.0
	v_add_f32_e32 v0, 1.0, v21
	v_max_f32_e32 v6, 0, v6
	v_rcp_f32_e32 v0, v0
	v_sqrt_f32_e32 v8, v6
	v_add_f32_e32 v6, 1.0, v7
	v_add_f32_e32 v7, v24, v124
	v_rcp_f32_e32 v6, v6
	v_mul_f32_e32 v7, 0xbfb8aa3b, v7
	v_exp_f32_e32 v7, v7
	v_mul_f32_e32 v0, v101, v0
	v_mul_f32_e32 v6, v128, v6
	v_mul_f32_e32 v21, v0, v8
	v_add_f32_e32 v8, v9, v113
	v_exp_f32_e32 v6, v6
	v_add_f32_e32 v0, 1.0, v7
	v_mul_f32_e32 v8, 0xbfb8aa3b, v8
	ds_read_b128 v[78:81], v89 offset:13760
	v_rcp_f32_e32 v0, v0
	v_exp_f32_e32 v8, v8
	v_fma_f32 v7, -v6, v6, 1.0
	v_max_f32_e32 v7, 0, v7
	v_mul_f32_e32 v0, v98, v0
	v_add_f32_e32 v8, 1.0, v8
	ds_read_b128 v[96:99], v89 offset:13792
	s_waitcnt lgkmcnt(1)
	v_add_f32_e32 v10, v10, v78
	v_sqrt_f32_e32 v7, v7
	v_rcp_f32_e32 v8, v8
	v_mul_f32_e32 v10, 0xbfb8aa3b, v10
	v_exp_f32_e32 v10, v10
	v_add_f32_e32 v9, v25, v125
	v_mul_f32_e32 v9, 0xbfb8aa3b, v9
	v_mul_f32_e32 v7, v0, v7
	v_mul_f32_e32 v0, v129, v8
	v_exp_f32_e32 v9, v9
	v_exp_f32_e32 v8, v0
	ds_read_b128 v[100:103], v89 offset:14016
	ds_read_b128 v[104:107], v89 offset:14272
	v_add_f32_e32 v10, 1.0, v10
	v_add_f32_e32 v11, v11, v79
	v_rcp_f32_e32 v10, v10
	v_mul_f32_e32 v11, 0xbfb8aa3b, v11
	v_exp_f32_e32 v11, v11
	v_add_f32_e32 v0, 1.0, v9
	v_fma_f32 v9, -v8, v8, 1.0
	s_waitcnt lgkmcnt(1)
	v_add_f32_e32 v22, v26, v100
	v_rcp_f32_e32 v0, v0
	v_max_f32_e32 v9, 0, v9
	v_mul_f32_e32 v22, 0xbfb8aa3b, v22
	s_waitcnt lgkmcnt(0)
	v_mul_f32_e32 v10, v104, v10
	v_sqrt_f32_e32 v9, v9
	v_exp_f32_e32 v23, v22
	v_exp_f32_e32 v22, v10
	v_add_f32_e32 v11, 1.0, v11
	v_rcp_f32_e32 v11, v11
	v_mul_f32_e32 v0, v92, v0
	v_mul_f32_e32 v9, v0, v9
	v_add_f32_e32 v0, 1.0, v23
	v_fma_f32 v10, -v22, v22, 1.0
	v_add_f32_e32 v23, v27, v101
	v_rcp_f32_e32 v0, v0
	v_max_f32_e32 v10, 0, v10
	v_mul_f32_e32 v23, 0xbfb8aa3b, v23
	v_mul_f32_e32 v11, v105, v11
	v_sqrt_f32_e32 v10, v10
	v_exp_f32_e32 v25, v23
	v_exp_f32_e32 v24, v11
	v_mul_f32_e32 v0, v94, v0
	v_mul_f32_e32 v23, v0, v10
	v_add_f32_e32 v0, 1.0, v25
	v_fma_f32 v10, -v24, v24, 1.0
	v_add_f32_e32 v11, v12, v80
	v_rcp_f32_e32 v0, v0
	v_mul_f32_e32 v11, 0xbfb8aa3b, v11
	v_max_f32_e32 v10, 0, v10
	v_exp_f32_e32 v11, v11
	v_sqrt_f32_e32 v12, v10
	v_mul_f32_e32 v0, v93, v0
	v_add_f32_e32 v14, v14, v96
	v_add_f32_e32 v10, 1.0, v11
	v_mul_f32_e32 v25, v0, v12
	v_add_f32_e32 v12, v13, v81
	v_rcp_f32_e32 v10, v10
	v_mul_f32_e32 v12, 0xbfb8aa3b, v12
	v_exp_f32_e32 v12, v12
	v_add_f32_e32 v11, v28, v102
	v_mul_f32_e32 v11, 0xbfb8aa3b, v11
	v_mul_f32_e32 v10, v106, v10
	v_exp_f32_e32 v11, v11
	v_exp_f32_e32 v10, v10
	v_add_f32_e32 v12, 1.0, v12
	v_rcp_f32_e32 v12, v12
	v_mul_f32_e32 v14, 0xbfb8aa3b, v14
	v_exp_f32_e32 v14, v14
	v_add_f32_e32 v0, 1.0, v11
	v_fma_f32 v11, -v10, v10, 1.0
	v_add_f32_e32 v13, v29, v103
	ds_read_b128 v[108:111], v89 offset:14048
	ds_read_b128 v[112:115], v89 offset:14304
	v_rcp_f32_e32 v0, v0
	v_max_f32_e32 v11, 0, v11
	v_mul_f32_e32 v13, 0xbfb8aa3b, v13
	v_mul_f32_e32 v12, v107, v12
	v_sqrt_f32_e32 v11, v11
	v_exp_f32_e32 v13, v13
	v_exp_f32_e32 v12, v12
	v_add_f32_e32 v14, 1.0, v14
	v_rcp_f32_e32 v14, v14
	v_mul_f32_e32 v0, v83, v0
	v_mul_f32_e32 v11, v0, v11
	v_add_f32_e32 v0, 1.0, v13
	v_fma_f32 v13, -v12, v12, 1.0
	s_waitcnt lgkmcnt(1)
; __device__ __forceinline__ float sigm(float x) { return __builtin_amdgcn_rcpf(1.f + __expf(-x)); }
; #define LAS __attribute__((address_space(3)))
; template <int PASS>
; __device__ __forceinline__ void lru_unit(const LruPtrs& args, LAS unsigned char* lds, int chunk, int bl, int g, int ck) {
;     ...
; #pragma unroll
;         for (int q = 0; q < 8; ++q) {
;             const f32x4 br = *(const LAS f32x4*)(PRM + 5 * 64 + 8 * q + 4 * hi), bi = *(const LAS f32x4*)(PRM + 6 * 64 + 8 * q + 4 * hi), cf = *(const LAS f32x4*)(PRM + 7 * 64 + 8 * q + 4 * hi);
; #pragma unroll
;             for (int p = 0; p < 4; ++p) { const int rb = q >> 2, r = (q & 3) * 4 + p;
;                 const float rr = pg8::sigm(ar[rb][r] + br[p]), ii = pg8::sigm(ai_[rb][r] + bi[p]);
;                 const float a0 = __builtin_amdgcn_exp2f(cf[p] * rr);
;                 av[q][p] = a0; uv[q][p] = __builtin_amdgcn_sqrtf(fmaxf(1.f - a0 * a0, 0.f)) * (ii * xc[q][p]); }
;         }
;     ...
;     if (PASS == 1) {
; #pragma unroll
;     for (int q = 0; q < 8; ++q)
;         asm volatile("s_nop 1\n\t"
;             LRU_STEP("row_shr:1 row_mask:0xf bank_mask:0xf") LRU_STEP("row_shr:2 row_mask:0xf bank_mask:0xf") LRU_STEP("row_shr:4 row_mask:0xf bank_mask:0xf")
;             LRU_STEP("row_shr:8 row_mask:0xf bank_mask:0xf") LRU_STEP("row_bcast:15 row_mask:0xa bank_mask:0xf")
;             : "+v"(uv[q][0]), "+v"(av[q][0]), "+v"(uv[q][1]), "+v"(av[q][1]), "+v"(uv[q][2]), "+v"(av[q][2]), "+v"(uv[q][3]), "+v"(av[q][3]));
	v_add_f32_e32 v26, v30, v108
	v_rcp_f32_e32 v0, v0
	v_max_f32_e32 v13, 0, v13
	v_mul_f32_e32 v26, 0xbfb8aa3b, v26
	s_waitcnt lgkmcnt(0)
	v_mul_f32_e32 v14, v112, v14
	v_add_f32_e32 v15, v15, v97
	v_sqrt_f32_e32 v13, v13
	v_exp_f32_e32 v27, v26
	v_exp_f32_e32 v26, v14
	v_mul_f32_e32 v15, 0xbfb8aa3b, v15
	v_exp_f32_e32 v15, v15
	v_mul_f32_e32 v0, v82, v0
	v_mul_f32_e32 v13, v0, v13
	v_add_f32_e32 v0, 1.0, v27
	v_fma_f32 v14, -v26, v26, 1.0
	v_rcp_f32_e32 v0, v0
	v_max_f32_e32 v14, 0, v14
	v_add_f32_e32 v27, v31, v109
	v_add_f32_e32 v15, 1.0, v15
	v_sqrt_f32_e32 v14, v14
	v_mul_f32_e32 v27, 0xbfb8aa3b, v27
	v_rcp_f32_e32 v15, v15
	v_exp_f32_e32 v28, v27
	v_mul_f32_e32 v0, v77, v0
	v_mul_f32_e32 v27, v0, v14
	v_mul_f32_e32 v14, v113, v15
	v_add_f32_e32 v0, 1.0, v28
	v_exp_f32_e32 v28, v14
	v_add_f32_e32 v14, v16, v98
	v_mul_f32_e32 v14, 0xbfb8aa3b, v14
	v_rcp_f32_e32 v0, v0
	v_fma_f32 v15, -v28, v28, 1.0
	v_exp_f32_e32 v14, v14
	v_max_f32_e32 v15, 0, v15
	v_sqrt_f32_e32 v15, v15
	v_mul_f32_e32 v0, v76, v0
	v_add_f32_e32 v14, 1.0, v14
	v_rcp_f32_e32 v14, v14
	v_mul_f32_e32 v29, v0, v15
	v_add_f32_e32 v15, v17, v99
	v_mul_f32_e32 v15, 0xbfb8aa3b, v15
	v_exp_f32_e32 v15, v15
	v_add_f32_e32 v16, v32, v110
	v_mul_f32_e32 v16, 0xbfb8aa3b, v16
	v_mul_f32_e32 v14, v114, v14
	v_exp_f32_e32 v16, v16
	v_exp_f32_e32 v14, v14
	v_add_f32_e32 v15, 1.0, v15
	v_rcp_f32_e32 v15, v15
	v_add_f32_e32 v0, 1.0, v16
	v_fma_f32 v16, -v14, v14, 1.0
	v_max_f32_e32 v17, 0, v16
	v_add_f32_e32 v16, v33, v111
	v_mul_f32_e32 v16, 0xbfb8aa3b, v16
	v_mul_f32_e32 v15, v115, v15
	v_exp_f32_e32 v30, v16
	v_exp_f32_e32 v16, v15
	v_rcp_f32_e32 v0, v0
	v_sqrt_f32_e32 v15, v17
	v_add_f32_e32 v17, 1.0, v30
	v_fma_f32 v30, -v16, v16, 1.0
	v_rcp_f32_e32 v17, v17
	v_max_f32_e32 v30, 0, v30
	v_sqrt_f32_e32 v30, v30
	v_mul_f32_e32 v0, v74, v0
	s_mov_b64 s[4:5], 0x29c00000
	v_mul_f32_e32 v15, v0, v15
	v_mul_f32_e32 v0, v75, v17
	v_lshl_add_u64 v[70:71], v[72:73], 0, s[4:5]
	v_mul_f32_e32 v17, v0, v30
	v_add_co_u32_e32 v72, vcc, s2, v72
	s_nop 1
	v_fmac_f32_dpp v67, v67, v66 row_shr:1 row_mask:0xf bank_mask:0xf
	v_fmac_f32_dpp v69, v69, v68 row_shr:1 row_mask:0xf bank_mask:0xf
	v_fmac_f32_dpp v35, v35, v34 row_shr:1 row_mask:0xf bank_mask:0xf
	v_fmac_f32_dpp v37, v37, v36 row_shr:1 row_mask:0xf bank_mask:0xf
	v_mul_f32_dpp v66, v66, v66 row_shr:1 row_mask:0xf bank_mask:0xf
	v_mul_f32_dpp v68, v68, v68 row_shr:1 row_mask:0xf bank_mask:0xf
	v_mul_f32_dpp v34, v34, v34 row_shr:1 row_mask:0xf bank_mask:0xf
	v_mul_f32_dpp v36, v36, v36 row_shr:1 row_mask:0xf bank_mask:0xf
	v_fmac_f32_dpp v67, v67, v66 row_shr:2 row_mask:0xf bank_mask:0xf
	v_fmac_f32_dpp v69, v69, v68 row_shr:2 row_mask:0xf bank_mask:0xf
	v_fmac_f32_dpp v35, v35, v34 row_shr:2 row_mask:0xf bank_mask:0xf
	v_fmac_f32_dpp v37, v37, v36 row_shr:2 row_mask:0xf bank_mask:0xf
	v_mul_f32_dpp v66, v66, v66 row_shr:2 row_mask:0xf bank_mask:0xf
	v_mul_f32_dpp v68, v68, v68 row_shr:2 row_mask:0xf bank_mask:0xf
	v_mul_f32_dpp v34, v34, v34 row_shr:2 row_mask:0xf bank_mask:0xf
	v_mul_f32_dpp v36, v36, v36 row_shr:2 row_mask:0xf bank_mask:0xf
	v_fmac_f32_dpp v67, v67, v66 row_shr:4 row_mask:0xf bank_mask:0xf
	v_fmac_f32_dpp v69, v69, v68 row_shr:4 row_mask:0xf bank_mask:0xf
	v_fmac_f32_dpp v35, v35, v34 row_shr:4 row_mask:0xf bank_mask:0xf
	v_fmac_f32_dpp v37, v37, v36 row_shr:4 row_mask:0xf bank_mask:0xf
	v_mul_f32_dpp v66, v66, v66 row_shr:4 row_mask:0xf bank_mask:0xf
	v_mul_f32_dpp v68, v68, v68 row_shr:4 row_mask:0xf bank_mask:0xf
	v_mul_f32_dpp v34, v34, v34 row_shr:4 row_mask:0xf bank_mask:0xf
	v_mul_f32_dpp v36, v36, v36 row_shr:4 row_mask:0xf bank_mask:0xf
	v_fmac_f32_dpp v67, v67, v66 row_shr:8 row_mask:0xf bank_mask:0xf
	v_fmac_f32_dpp v69, v69, v68 row_shr:8 row_mask:0xf bank_mask:0xf
	v_fmac_f32_dpp v35, v35, v34 row_shr:8 row_mask:0xf bank_mask:0xf
	v_fmac_f32_dpp v37, v37, v36 row_shr:8 row_mask:0xf bank_mask:0xf
	v_mul_f32_dpp v66, v66, v66 row_shr:8 row_mask:0xf bank_mask:0xf
	v_mul_f32_dpp v68, v68, v68 row_shr:8 row_mask:0xf bank_mask:0xf
	v_mul_f32_dpp v34, v34, v34 row_shr:8 row_mask:0xf bank_mask:0xf
	v_mul_f32_dpp v36, v36, v36 row_shr:8 row_mask:0xf bank_mask:0xf
	v_fmac_f32_dpp v67, v67, v66 row_bcast:15 row_mask:0xa bank_mask:0xf
	v_fmac_f32_dpp v69, v69, v68 row_bcast:15 row_mask:0xa bank_mask:0xf
	v_fmac_f32_dpp v35, v35, v34 row_bcast:15 row_mask:0xa bank_mask:0xf
	v_fmac_f32_dpp v37, v37, v36 row_bcast:15 row_mask:0xa bank_mask:0xf
	v_mul_f32_dpp v66, v66, v66 row_bcast:15 row_mask:0xa bank_mask:0xf
	v_mul_f32_dpp v68, v68, v68 row_bcast:15 row_mask:0xa bank_mask:0xf
	v_mul_f32_dpp v34, v34, v34 row_bcast:15 row_mask:0xa bank_mask:0xf
	v_mul_f32_dpp v36, v36, v36 row_bcast:15 row_mask:0xa bank_mask:0xf

; template <int PASS>
; __device__ __forceinline__ void lru_unit(const LruPtrs& args, LAS unsigned char* lds, int chunk, int bl, int g, int ck) {
;     ...
;     if (PASS == 1) {
; #pragma unroll
;     for (int q = 0; q < 8; ++q)
;         asm volatile("s_nop 1\n\t"
;             LRU_STEP("row_shr:1 row_mask:0xf bank_mask:0xf") LRU_STEP("row_shr:2 row_mask:0xf bank_mask:0xf") LRU_STEP("row_shr:4 row_mask:0xf bank_mask:0xf")
;             LRU_STEP("row_shr:8 row_mask:0xf bank_mask:0xf") LRU_STEP("row_bcast:15 row_mask:0xa bank_mask:0xf")
;             : "+v"(uv[q][0]), "+v"(av[q][0]), "+v"(uv[q][1]), "+v"(av[q][1]), "+v"(uv[q][2]), "+v"(av[q][2]), "+v"(uv[q][3]), "+v"(av[q][3]));
	s_nop 1
	v_fmac_f32_dpp v51, v51, v50 row_shr:1 row_mask:0xf bank_mask:0xf
	v_fmac_f32_dpp v53, v53, v52 row_shr:1 row_mask:0xf bank_mask:0xf
	v_fmac_f32_dpp v39, v39, v38 row_shr:1 row_mask:0xf bank_mask:0xf
	v_fmac_f32_dpp v41, v41, v40 row_shr:1 row_mask:0xf bank_mask:0xf
	v_mul_f32_dpp v50, v50, v50 row_shr:1 row_mask:0xf bank_mask:0xf
	v_mul_f32_dpp v52, v52, v52 row_shr:1 row_mask:0xf bank_mask:0xf
	v_mul_f32_dpp v38, v38, v38 row_shr:1 row_mask:0xf bank_mask:0xf
	v_mul_f32_dpp v40, v40, v40 row_shr:1 row_mask:0xf bank_mask:0xf
	v_fmac_f32_dpp v51, v51, v50 row_shr:2 row_mask:0xf bank_mask:0xf
	v_fmac_f32_dpp v53, v53, v52 row_shr:2 row_mask:0xf bank_mask:0xf
	v_fmac_f32_dpp v39, v39, v38 row_shr:2 row_mask:0xf bank_mask:0xf
	v_fmac_f32_dpp v41, v41, v40 row_shr:2 row_mask:0xf bank_mask:0xf
	v_mul_f32_dpp v50, v50, v50 row_shr:2 row_mask:0xf bank_mask:0xf
	v_mul_f32_dpp v52, v52, v52 row_shr:2 row_mask:0xf bank_mask:0xf
	v_mul_f32_dpp v38, v38, v38 row_shr:2 row_mask:0xf bank_mask:0xf
	v_mul_f32_dpp v40, v40, v40 row_shr:2 row_mask:0xf bank_mask:0xf
	v_fmac_f32_dpp v51, v51, v50 row_shr:4 row_mask:0xf bank_mask:0xf
	v_fmac_f32_dpp v53, v53, v52 row_shr:4 row_mask:0xf bank_mask:0xf
	v_fmac_f32_dpp v39, v39, v38 row_shr:4 row_mask:0xf bank_mask:0xf
	v_fmac_f32_dpp v41, v41, v40 row_shr:4 row_mask:0xf bank_mask:0xf
	v_mul_f32_dpp v50, v50, v50 row_shr:4 row_mask:0xf bank_mask:0xf
	v_mul_f32_dpp v52, v52, v52 row_shr:4 row_mask:0xf bank_mask:0xf
	v_mul_f32_dpp v38, v38, v38 row_shr:4 row_mask:0xf bank_mask:0xf
	v_mul_f32_dpp v40, v40, v40 row_shr:4 row_mask:0xf bank_mask:0xf
	v_fmac_f32_dpp v51, v51, v50 row_shr:8 row_mask:0xf bank_mask:0xf
	v_fmac_f32_dpp v53, v53, v52 row_shr:8 row_mask:0xf bank_mask:0xf
	v_fmac_f32_dpp v39, v39, v38 row_shr:8 row_mask:0xf bank_mask:0xf
	v_fmac_f32_dpp v41, v41, v40 row_shr:8 row_mask:0xf bank_mask:0xf
	v_mul_f32_dpp v50, v50, v50 row_shr:8 row_mask:0xf bank_mask:0xf
	v_mul_f32_dpp v52, v52, v52 row_shr:8 row_mask:0xf bank_mask:0xf
	v_mul_f32_dpp v38, v38, v38 row_shr:8 row_mask:0xf bank_mask:0xf
	v_mul_f32_dpp v40, v40, v40 row_shr:8 row_mask:0xf bank_mask:0xf
	v_fmac_f32_dpp v51, v51, v50 row_bcast:15 row_mask:0xa bank_mask:0xf
	v_fmac_f32_dpp v53, v53, v52 row_bcast:15 row_mask:0xa bank_mask:0xf
	v_fmac_f32_dpp v39, v39, v38 row_bcast:15 row_mask:0xa bank_mask:0xf
	v_fmac_f32_dpp v41, v41, v40 row_bcast:15 row_mask:0xa bank_mask:0xf
	v_mul_f32_dpp v50, v50, v50 row_bcast:15 row_mask:0xa bank_mask:0xf
	v_mul_f32_dpp v52, v52, v52 row_bcast:15 row_mask:0xa bank_mask:0xf
	v_mul_f32_dpp v38, v38, v38 row_bcast:15 row_mask:0xa bank_mask:0xf
	v_mul_f32_dpp v40, v40, v40 row_bcast:15 row_mask:0xa bank_mask:0xf

; template <int PASS>
; __device__ __forceinline__ void lru_unit(const LruPtrs& args, LAS unsigned char* lds, int chunk, int bl, int g, int ck) {
;     ...
;     if (PASS == 1) {
; #pragma unroll
;     for (int q = 0; q < 8; ++q)
;         asm volatile("s_nop 1\n\t"
;             LRU_STEP("row_shr:1 row_mask:0xf bank_mask:0xf") LRU_STEP("row_shr:2 row_mask:0xf bank_mask:0xf") LRU_STEP("row_shr:4 row_mask:0xf bank_mask:0xf")
;             LRU_STEP("row_shr:8 row_mask:0xf bank_mask:0xf") LRU_STEP("row_bcast:15 row_mask:0xa bank_mask:0xf")
;             : "+v"(uv[q][0]), "+v"(av[q][0]), "+v"(uv[q][1]), "+v"(av[q][1]), "+v"(uv[q][2]), "+v"(av[q][2]), "+v"(uv[q][3]), "+v"(av[q][3]));
	s_nop 1
	v_fmac_f32_dpp v55, v55, v54 row_shr:1 row_mask:0xf bank_mask:0xf
	v_fmac_f32_dpp v57, v57, v56 row_shr:1 row_mask:0xf bank_mask:0xf
	v_fmac_f32_dpp v43, v43, v42 row_shr:1 row_mask:0xf bank_mask:0xf
	v_fmac_f32_dpp v45, v45, v44 row_shr:1 row_mask:0xf bank_mask:0xf
	v_mul_f32_dpp v54, v54, v54 row_shr:1 row_mask:0xf bank_mask:0xf
	v_mul_f32_dpp v56, v56, v56 row_shr:1 row_mask:0xf bank_mask:0xf
	v_mul_f32_dpp v42, v42, v42 row_shr:1 row_mask:0xf bank_mask:0xf
	v_mul_f32_dpp v44, v44, v44 row_shr:1 row_mask:0xf bank_mask:0xf
	v_fmac_f32_dpp v55, v55, v54 row_shr:2 row_mask:0xf bank_mask:0xf
	v_fmac_f32_dpp v57, v57, v56 row_shr:2 row_mask:0xf bank_mask:0xf
	v_fmac_f32_dpp v43, v43, v42 row_shr:2 row_mask:0xf bank_mask:0xf
	v_fmac_f32_dpp v45, v45, v44 row_shr:2 row_mask:0xf bank_mask:0xf
	v_mul_f32_dpp v54, v54, v54 row_shr:2 row_mask:0xf bank_mask:0xf
	v_mul_f32_dpp v56, v56, v56 row_shr:2 row_mask:0xf bank_mask:0xf
	v_mul_f32_dpp v42, v42, v42 row_shr:2 row_mask:0xf bank_mask:0xf
	v_mul_f32_dpp v44, v44, v44 row_shr:2 row_mask:0xf bank_mask:0xf
	v_fmac_f32_dpp v55, v55, v54 row_shr:4 row_mask:0xf bank_mask:0xf
	v_fmac_f32_dpp v57, v57, v56 row_shr:4 row_mask:0xf bank_mask:0xf
	v_fmac_f32_dpp v43, v43, v42 row_shr:4 row_mask:0xf bank_mask:0xf
	v_fmac_f32_dpp v45, v45, v44 row_shr:4 row_mask:0xf bank_mask:0xf
	v_mul_f32_dpp v54, v54, v54 row_shr:4 row_mask:0xf bank_mask:0xf
	v_mul_f32_dpp v56, v56, v56 row_shr:4 row_mask:0xf bank_mask:0xf
	v_mul_f32_dpp v42, v42, v42 row_shr:4 row_mask:0xf bank_mask:0xf
	v_mul_f32_dpp v44, v44, v44 row_shr:4 row_mask:0xf bank_mask:0xf
	v_fmac_f32_dpp v55, v55, v54 row_shr:8 row_mask:0xf bank_mask:0xf
	v_fmac_f32_dpp v57, v57, v56 row_shr:8 row_mask:0xf bank_mask:0xf
	v_fmac_f32_dpp v43, v43, v42 row_shr:8 row_mask:0xf bank_mask:0xf
	v_fmac_f32_dpp v45, v45, v44 row_shr:8 row_mask:0xf bank_mask:0xf
	v_mul_f32_dpp v54, v54, v54 row_shr:8 row_mask:0xf bank_mask:0xf
	v_mul_f32_dpp v56, v56, v56 row_shr:8 row_mask:0xf bank_mask:0xf
	v_mul_f32_dpp v42, v42, v42 row_shr:8 row_mask:0xf bank_mask:0xf
	v_mul_f32_dpp v44, v44, v44 row_shr:8 row_mask:0xf bank_mask:0xf
	v_fmac_f32_dpp v55, v55, v54 row_bcast:15 row_mask:0xa bank_mask:0xf
	v_fmac_f32_dpp v57, v57, v56 row_bcast:15 row_mask:0xa bank_mask:0xf
	v_fmac_f32_dpp v43, v43, v42 row_bcast:15 row_mask:0xa bank_mask:0xf
	v_fmac_f32_dpp v45, v45, v44 row_bcast:15 row_mask:0xa bank_mask:0xf
	v_mul_f32_dpp v54, v54, v54 row_bcast:15 row_mask:0xa bank_mask:0xf
	v_mul_f32_dpp v56, v56, v56 row_bcast:15 row_mask:0xa bank_mask:0xf
	v_mul_f32_dpp v42, v42, v42 row_bcast:15 row_mask:0xa bank_mask:0xf
	v_mul_f32_dpp v44, v44, v44 row_bcast:15 row_mask:0xa bank_mask:0xf

; template <int PASS>
; __device__ __forceinline__ void lru_unit(const LruPtrs& args, LAS unsigned char* lds, int chunk, int bl, int g, int ck) {
;     ...
;     if (PASS == 1) {
; #pragma unroll
;     for (int q = 0; q < 8; ++q)
;         asm volatile("s_nop 1\n\t"
;             LRU_STEP("row_shr:1 row_mask:0xf bank_mask:0xf") LRU_STEP("row_shr:2 row_mask:0xf bank_mask:0xf") LRU_STEP("row_shr:4 row_mask:0xf bank_mask:0xf")
;             LRU_STEP("row_shr:8 row_mask:0xf bank_mask:0xf") LRU_STEP("row_bcast:15 row_mask:0xa bank_mask:0xf")
;             : "+v"(uv[q][0]), "+v"(av[q][0]), "+v"(uv[q][1]), "+v"(av[q][1]), "+v"(uv[q][2]), "+v"(av[q][2]), "+v"(uv[q][3]), "+v"(av[q][3]));
	s_nop 1
	v_fmac_f32_dpp v59, v59, v58 row_shr:1 row_mask:0xf bank_mask:0xf
	v_fmac_f32_dpp v61, v61, v60 row_shr:1 row_mask:0xf bank_mask:0xf
	v_fmac_f32_dpp v47, v47, v46 row_shr:1 row_mask:0xf bank_mask:0xf
	v_fmac_f32_dpp v49, v49, v48 row_shr:1 row_mask:0xf bank_mask:0xf
	v_mul_f32_dpp v58, v58, v58 row_shr:1 row_mask:0xf bank_mask:0xf
	v_mul_f32_dpp v60, v60, v60 row_shr:1 row_mask:0xf bank_mask:0xf
	v_mul_f32_dpp v46, v46, v46 row_shr:1 row_mask:0xf bank_mask:0xf
	v_mul_f32_dpp v48, v48, v48 row_shr:1 row_mask:0xf bank_mask:0xf
	v_fmac_f32_dpp v59, v59, v58 row_shr:2 row_mask:0xf bank_mask:0xf
	v_fmac_f32_dpp v61, v61, v60 row_shr:2 row_mask:0xf bank_mask:0xf
	v_fmac_f32_dpp v47, v47, v46 row_shr:2 row_mask:0xf bank_mask:0xf
	v_fmac_f32_dpp v49, v49, v48 row_shr:2 row_mask:0xf bank_mask:0xf
	v_mul_f32_dpp v58, v58, v58 row_shr:2 row_mask:0xf bank_mask:0xf
	v_mul_f32_dpp v60, v60, v60 row_shr:2 row_mask:0xf bank_mask:0xf
	v_mul_f32_dpp v46, v46, v46 row_shr:2 row_mask:0xf bank_mask:0xf
	v_mul_f32_dpp v48, v48, v48 row_shr:2 row_mask:0xf bank_mask:0xf
	v_fmac_f32_dpp v59, v59, v58 row_shr:4 row_mask:0xf bank_mask:0xf
	v_fmac_f32_dpp v61, v61, v60 row_shr:4 row_mask:0xf bank_mask:0xf
	v_fmac_f32_dpp v47, v47, v46 row_shr:4 row_mask:0xf bank_mask:0xf
	v_fmac_f32_dpp v49, v49, v48 row_shr:4 row_mask:0xf bank_mask:0xf
	v_mul_f32_dpp v58, v58, v58 row_shr:4 row_mask:0xf bank_mask:0xf
	v_mul_f32_dpp v60, v60, v60 row_shr:4 row_mask:0xf bank_mask:0xf
	v_mul_f32_dpp v46, v46, v46 row_shr:4 row_mask:0xf bank_mask:0xf
	v_mul_f32_dpp v48, v48, v48 row_shr:4 row_mask:0xf bank_mask:0xf
	v_fmac_f32_dpp v59, v59, v58 row_shr:8 row_mask:0xf bank_mask:0xf
	v_fmac_f32_dpp v61, v61, v60 row_shr:8 row_mask:0xf bank_mask:0xf
	v_fmac_f32_dpp v47, v47, v46 row_shr:8 row_mask:0xf bank_mask:0xf
	v_fmac_f32_dpp v49, v49, v48 row_shr:8 row_mask:0xf bank_mask:0xf
	v_mul_f32_dpp v58, v58, v58 row_shr:8 row_mask:0xf bank_mask:0xf
	v_mul_f32_dpp v60, v60, v60 row_shr:8 row_mask:0xf bank_mask:0xf
	v_mul_f32_dpp v46, v46, v46 row_shr:8 row_mask:0xf bank_mask:0xf
	v_mul_f32_dpp v48, v48, v48 row_shr:8 row_mask:0xf bank_mask:0xf
	v_fmac_f32_dpp v59, v59, v58 row_bcast:15 row_mask:0xa bank_mask:0xf
	v_fmac_f32_dpp v61, v61, v60 row_bcast:15 row_mask:0xa bank_mask:0xf
	v_fmac_f32_dpp v47, v47, v46 row_bcast:15 row_mask:0xa bank_mask:0xf
	v_fmac_f32_dpp v49, v49, v48 row_bcast:15 row_mask:0xa bank_mask:0xf
	v_mul_f32_dpp v58, v58, v58 row_bcast:15 row_mask:0xa bank_mask:0xf
	v_mul_f32_dpp v60, v60, v60 row_bcast:15 row_mask:0xa bank_mask:0xf
	v_mul_f32_dpp v46, v46, v46 row_bcast:15 row_mask:0xa bank_mask:0xf
	v_mul_f32_dpp v48, v48, v48 row_bcast:15 row_mask:0xa bank_mask:0xf

; template <int PASS>
; __device__ __forceinline__ void lru_unit(const LruPtrs& args, LAS unsigned char* lds, int chunk, int bl, int g, int ck) {
;     ...
;     if (PASS == 1) {
; #pragma unroll
;     for (int q = 0; q < 8; ++q)
;         asm volatile("s_nop 1\n\t"
;             LRU_STEP("row_shr:1 row_mask:0xf bank_mask:0xf") LRU_STEP("row_shr:2 row_mask:0xf bank_mask:0xf") LRU_STEP("row_shr:4 row_mask:0xf bank_mask:0xf")
;             LRU_STEP("row_shr:8 row_mask:0xf bank_mask:0xf") LRU_STEP("row_bcast:15 row_mask:0xa bank_mask:0xf")
;             : "+v"(uv[q][0]), "+v"(av[q][0]), "+v"(uv[q][1]), "+v"(av[q][1]), "+v"(uv[q][2]), "+v"(av[q][2]), "+v"(uv[q][3]), "+v"(av[q][3]));
	s_nop 1
	v_fmac_f32_dpp v63, v63, v62 row_shr:1 row_mask:0xf bank_mask:0xf
	v_fmac_f32_dpp v65, v65, v64 row_shr:1 row_mask:0xf bank_mask:0xf
	v_fmac_f32_dpp v3, v3, v2 row_shr:1 row_mask:0xf bank_mask:0xf
	v_fmac_f32_dpp v5, v5, v4 row_shr:1 row_mask:0xf bank_mask:0xf
	v_mul_f32_dpp v62, v62, v62 row_shr:1 row_mask:0xf bank_mask:0xf
	v_mul_f32_dpp v64, v64, v64 row_shr:1 row_mask:0xf bank_mask:0xf
	v_mul_f32_dpp v2, v2, v2 row_shr:1 row_mask:0xf bank_mask:0xf
	v_mul_f32_dpp v4, v4, v4 row_shr:1 row_mask:0xf bank_mask:0xf
	v_fmac_f32_dpp v63, v63, v62 row_shr:2 row_mask:0xf bank_mask:0xf
	v_fmac_f32_dpp v65, v65, v64 row_shr:2 row_mask:0xf bank_mask:0xf
	v_fmac_f32_dpp v3, v3, v2 row_shr:2 row_mask:0xf bank_mask:0xf
	v_fmac_f32_dpp v5, v5, v4 row_shr:2 row_mask:0xf bank_mask:0xf
	v_mul_f32_dpp v62, v62, v62 row_shr:2 row_mask:0xf bank_mask:0xf
	v_mul_f32_dpp v64, v64, v64 row_shr:2 row_mask:0xf bank_mask:0xf
	v_mul_f32_dpp v2, v2, v2 row_shr:2 row_mask:0xf bank_mask:0xf
	v_mul_f32_dpp v4, v4, v4 row_shr:2 row_mask:0xf bank_mask:0xf
	v_fmac_f32_dpp v63, v63, v62 row_shr:4 row_mask:0xf bank_mask:0xf
	v_fmac_f32_dpp v65, v65, v64 row_shr:4 row_mask:0xf bank_mask:0xf
	v_fmac_f32_dpp v3, v3, v2 row_shr:4 row_mask:0xf bank_mask:0xf
	v_fmac_f32_dpp v5, v5, v4 row_shr:4 row_mask:0xf bank_mask:0xf
	v_mul_f32_dpp v62, v62, v62 row_shr:4 row_mask:0xf bank_mask:0xf
	v_mul_f32_dpp v64, v64, v64 row_shr:4 row_mask:0xf bank_mask:0xf
	v_mul_f32_dpp v2, v2, v2 row_shr:4 row_mask:0xf bank_mask:0xf
	v_mul_f32_dpp v4, v4, v4 row_shr:4 row_mask:0xf bank_mask:0xf
	v_fmac_f32_dpp v63, v63, v62 row_shr:8 row_mask:0xf bank_mask:0xf
	v_fmac_f32_dpp v65, v65, v64 row_shr:8 row_mask:0xf bank_mask:0xf
	v_fmac_f32_dpp v3, v3, v2 row_shr:8 row_mask:0xf bank_mask:0xf
	v_fmac_f32_dpp v5, v5, v4 row_shr:8 row_mask:0xf bank_mask:0xf
	v_mul_f32_dpp v62, v62, v62 row_shr:8 row_mask:0xf bank_mask:0xf
	v_mul_f32_dpp v64, v64, v64 row_shr:8 row_mask:0xf bank_mask:0xf
	v_mul_f32_dpp v2, v2, v2 row_shr:8 row_mask:0xf bank_mask:0xf
	v_mul_f32_dpp v4, v4, v4 row_shr:8 row_mask:0xf bank_mask:0xf
	v_fmac_f32_dpp v63, v63, v62 row_bcast:15 row_mask:0xa bank_mask:0xf
	v_fmac_f32_dpp v65, v65, v64 row_bcast:15 row_mask:0xa bank_mask:0xf
	v_fmac_f32_dpp v3, v3, v2 row_bcast:15 row_mask:0xa bank_mask:0xf
	v_fmac_f32_dpp v5, v5, v4 row_bcast:15 row_mask:0xa bank_mask:0xf
	v_mul_f32_dpp v62, v62, v62 row_bcast:15 row_mask:0xa bank_mask:0xf
	v_mul_f32_dpp v64, v64, v64 row_bcast:15 row_mask:0xa bank_mask:0xf
	v_mul_f32_dpp v2, v2, v2 row_bcast:15 row_mask:0xa bank_mask:0xf
	v_mul_f32_dpp v4, v4, v4 row_bcast:15 row_mask:0xa bank_mask:0xf

; template <int PASS>
; __device__ __forceinline__ void lru_unit(const LruPtrs& args, LAS unsigned char* lds, int chunk, int bl, int g, int ck) {
;     ...
;     if (PASS == 1) {
; #pragma unroll
;     for (int q = 0; q < 8; ++q)
;         asm volatile("s_nop 1\n\t"
;             LRU_STEP("row_shr:1 row_mask:0xf bank_mask:0xf") LRU_STEP("row_shr:2 row_mask:0xf bank_mask:0xf") LRU_STEP("row_shr:4 row_mask:0xf bank_mask:0xf")
;             LRU_STEP("row_shr:8 row_mask:0xf bank_mask:0xf") LRU_STEP("row_bcast:15 row_mask:0xa bank_mask:0xf")
;             : "+v"(uv[q][0]), "+v"(av[q][0]), "+v"(uv[q][1]), "+v"(av[q][1]), "+v"(uv[q][2]), "+v"(av[q][2]), "+v"(uv[q][3]), "+v"(av[q][3]));
	s_nop 1
	v_fmac_f32_dpp v19, v19, v18 row_shr:1 row_mask:0xf bank_mask:0xf
	v_fmac_f32_dpp v21, v21, v20 row_shr:1 row_mask:0xf bank_mask:0xf
	v_fmac_f32_dpp v7, v7, v6 row_shr:1 row_mask:0xf bank_mask:0xf
	v_fmac_f32_dpp v9, v9, v8 row_shr:1 row_mask:0xf bank_mask:0xf
	v_mul_f32_dpp v18, v18, v18 row_shr:1 row_mask:0xf bank_mask:0xf
	v_mul_f32_dpp v20, v20, v20 row_shr:1 row_mask:0xf bank_mask:0xf
	v_mul_f32_dpp v6, v6, v6 row_shr:1 row_mask:0xf bank_mask:0xf
	v_mul_f32_dpp v8, v8, v8 row_shr:1 row_mask:0xf bank_mask:0xf
	v_fmac_f32_dpp v19, v19, v18 row_shr:2 row_mask:0xf bank_mask:0xf
	v_fmac_f32_dpp v21, v21, v20 row_shr:2 row_mask:0xf bank_mask:0xf
	v_fmac_f32_dpp v7, v7, v6 row_shr:2 row_mask:0xf bank_mask:0xf
	v_fmac_f32_dpp v9, v9, v8 row_shr:2 row_mask:0xf bank_mask:0xf
	v_mul_f32_dpp v18, v18, v18 row_shr:2 row_mask:0xf bank_mask:0xf
	v_mul_f32_dpp v20, v20, v20 row_shr:2 row_mask:0xf bank_mask:0xf
	v_mul_f32_dpp v6, v6, v6 row_shr:2 row_mask:0xf bank_mask:0xf
	v_mul_f32_dpp v8, v8, v8 row_shr:2 row_mask:0xf bank_mask:0xf
	v_fmac_f32_dpp v19, v19, v18 row_shr:4 row_mask:0xf bank_mask:0xf
	v_fmac_f32_dpp v21, v21, v20 row_shr:4 row_mask:0xf bank_mask:0xf
	v_fmac_f32_dpp v7, v7, v6 row_shr:4 row_mask:0xf bank_mask:0xf
	v_fmac_f32_dpp v9, v9, v8 row_shr:4 row_mask:0xf bank_mask:0xf
	v_mul_f32_dpp v18, v18, v18 row_shr:4 row_mask:0xf bank_mask:0xf
	v_mul_f32_dpp v20, v20, v20 row_shr:4 row_mask:0xf bank_mask:0xf
	v_mul_f32_dpp v6, v6, v6 row_shr:4 row_mask:0xf bank_mask:0xf
	v_mul_f32_dpp v8, v8, v8 row_shr:4 row_mask:0xf bank_mask:0xf
	v_fmac_f32_dpp v19, v19, v18 row_shr:8 row_mask:0xf bank_mask:0xf
	v_fmac_f32_dpp v21, v21, v20 row_shr:8 row_mask:0xf bank_mask:0xf
	v_fmac_f32_dpp v7, v7, v6 row_shr:8 row_mask:0xf bank_mask:0xf
	v_fmac_f32_dpp v9, v9, v8 row_shr:8 row_mask:0xf bank_mask:0xf
	v_mul_f32_dpp v18, v18, v18 row_shr:8 row_mask:0xf bank_mask:0xf
	v_mul_f32_dpp v20, v20, v20 row_shr:8 row_mask:0xf bank_mask:0xf
	v_mul_f32_dpp v6, v6, v6 row_shr:8 row_mask:0xf bank_mask:0xf
	v_mul_f32_dpp v8, v8, v8 row_shr:8 row_mask:0xf bank_mask:0xf
	v_fmac_f32_dpp v19, v19, v18 row_bcast:15 row_mask:0xa bank_mask:0xf
	v_fmac_f32_dpp v21, v21, v20 row_bcast:15 row_mask:0xa bank_mask:0xf
	v_fmac_f32_dpp v7, v7, v6 row_bcast:15 row_mask:0xa bank_mask:0xf
	v_fmac_f32_dpp v9, v9, v8 row_bcast:15 row_mask:0xa bank_mask:0xf
	v_mul_f32_dpp v18, v18, v18 row_bcast:15 row_mask:0xa bank_mask:0xf
	v_mul_f32_dpp v20, v20, v20 row_bcast:15 row_mask:0xa bank_mask:0xf
	v_mul_f32_dpp v6, v6, v6 row_bcast:15 row_mask:0xa bank_mask:0xf
	v_mul_f32_dpp v8, v8, v8 row_bcast:15 row_mask:0xa bank_mask:0xf

; template <int PASS>
; __device__ __forceinline__ void lru_unit(const LruPtrs& args, LAS unsigned char* lds, int chunk, int bl, int g, int ck) {
;     ...
;     if (PASS == 1) {
; #pragma unroll
;     for (int q = 0; q < 8; ++q)
;         asm volatile("s_nop 1\n\t"
;             LRU_STEP("row_shr:1 row_mask:0xf bank_mask:0xf") LRU_STEP("row_shr:2 row_mask:0xf bank_mask:0xf") LRU_STEP("row_shr:4 row_mask:0xf bank_mask:0xf")
;             LRU_STEP("row_shr:8 row_mask:0xf bank_mask:0xf") LRU_STEP("row_bcast:15 row_mask:0xa bank_mask:0xf")
;             : "+v"(uv[q][0]), "+v"(av[q][0]), "+v"(uv[q][1]), "+v"(av[q][1]), "+v"(uv[q][2]), "+v"(av[q][2]), "+v"(uv[q][3]), "+v"(av[q][3]));
	s_nop 1
	v_fmac_f32_dpp v23, v23, v22 row_shr:1 row_mask:0xf bank_mask:0xf
	v_fmac_f32_dpp v25, v25, v24 row_shr:1 row_mask:0xf bank_mask:0xf
	v_fmac_f32_dpp v11, v11, v10 row_shr:1 row_mask:0xf bank_mask:0xf
	v_fmac_f32_dpp v13, v13, v12 row_shr:1 row_mask:0xf bank_mask:0xf
	v_mul_f32_dpp v22, v22, v22 row_shr:1 row_mask:0xf bank_mask:0xf
	v_mul_f32_dpp v24, v24, v24 row_shr:1 row_mask:0xf bank_mask:0xf
	v_mul_f32_dpp v10, v10, v10 row_shr:1 row_mask:0xf bank_mask:0xf
	v_mul_f32_dpp v12, v12, v12 row_shr:1 row_mask:0xf bank_mask:0xf
	v_fmac_f32_dpp v23, v23, v22 row_shr:2 row_mask:0xf bank_mask:0xf
	v_fmac_f32_dpp v25, v25, v24 row_shr:2 row_mask:0xf bank_mask:0xf
	v_fmac_f32_dpp v11, v11, v10 row_shr:2 row_mask:0xf bank_mask:0xf
	v_fmac_f32_dpp v13, v13, v12 row_shr:2 row_mask:0xf bank_mask:0xf
	v_mul_f32_dpp v22, v22, v22 row_shr:2 row_mask:0xf bank_mask:0xf
	v_mul_f32_dpp v24, v24, v24 row_shr:2 row_mask:0xf bank_mask:0xf
	v_mul_f32_dpp v10, v10, v10 row_shr:2 row_mask:0xf bank_mask:0xf
	v_mul_f32_dpp v12, v12, v12 row_shr:2 row_mask:0xf bank_mask:0xf
	v_fmac_f32_dpp v23, v23, v22 row_shr:4 row_mask:0xf bank_mask:0xf
	v_fmac_f32_dpp v25, v25, v24 row_shr:4 row_mask:0xf bank_mask:0xf
	v_fmac_f32_dpp v11, v11, v10 row_shr:4 row_mask:0xf bank_mask:0xf
	v_fmac_f32_dpp v13, v13, v12 row_shr:4 row_mask:0xf bank_mask:0xf
	v_mul_f32_dpp v22, v22, v22 row_shr:4 row_mask:0xf bank_mask:0xf
	v_mul_f32_dpp v24, v24, v24 row_shr:4 row_mask:0xf bank_mask:0xf
	v_mul_f32_dpp v10, v10, v10 row_shr:4 row_mask:0xf bank_mask:0xf
	v_mul_f32_dpp v12, v12, v12 row_shr:4 row_mask:0xf bank_mask:0xf
	v_fmac_f32_dpp v23, v23, v22 row_shr:8 row_mask:0xf bank_mask:0xf
	v_fmac_f32_dpp v25, v25, v24 row_shr:8 row_mask:0xf bank_mask:0xf
	v_fmac_f32_dpp v11, v11, v10 row_shr:8 row_mask:0xf bank_mask:0xf
	v_fmac_f32_dpp v13, v13, v12 row_shr:8 row_mask:0xf bank_mask:0xf
	v_mul_f32_dpp v22, v22, v22 row_shr:8 row_mask:0xf bank_mask:0xf
	v_mul_f32_dpp v24, v24, v24 row_shr:8 row_mask:0xf bank_mask:0xf
	v_mul_f32_dpp v10, v10, v10 row_shr:8 row_mask:0xf bank_mask:0xf
	v_mul_f32_dpp v12, v12, v12 row_shr:8 row_mask:0xf bank_mask:0xf
	v_fmac_f32_dpp v23, v23, v22 row_bcast:15 row_mask:0xa bank_mask:0xf
	v_fmac_f32_dpp v25, v25, v24 row_bcast:15 row_mask:0xa bank_mask:0xf
	v_fmac_f32_dpp v11, v11, v10 row_bcast:15 row_mask:0xa bank_mask:0xf
	v_fmac_f32_dpp v13, v13, v12 row_bcast:15 row_mask:0xa bank_mask:0xf
	v_mul_f32_dpp v22, v22, v22 row_bcast:15 row_mask:0xa bank_mask:0xf
	v_mul_f32_dpp v24, v24, v24 row_bcast:15 row_mask:0xa bank_mask:0xf
	v_mul_f32_dpp v10, v10, v10 row_bcast:15 row_mask:0xa bank_mask:0xf
	v_mul_f32_dpp v12, v12, v12 row_bcast:15 row_mask:0xa bank_mask:0xf

; template <int PASS>
; __device__ __forceinline__ void lru_unit(const LruPtrs& args, LAS unsigned char* lds, int chunk, int bl, int g, int ck) {
;     ...
;     if (PASS == 1) {
; #pragma unroll
;     for (int q = 0; q < 8; ++q)
;         asm volatile("s_nop 1\n\t"
;             LRU_STEP("row_shr:1 row_mask:0xf bank_mask:0xf") LRU_STEP("row_shr:2 row_mask:0xf bank_mask:0xf") LRU_STEP("row_shr:4 row_mask:0xf bank_mask:0xf")
;             LRU_STEP("row_shr:8 row_mask:0xf bank_mask:0xf") LRU_STEP("row_bcast:15 row_mask:0xa bank_mask:0xf")
;             : "+v"(uv[q][0]), "+v"(av[q][0]), "+v"(uv[q][1]), "+v"(av[q][1]), "+v"(uv[q][2]), "+v"(av[q][2]), "+v"(uv[q][3]), "+v"(av[q][3]));
	s_nop 1
	v_fmac_f32_dpp v27, v27, v26 row_shr:1 row_mask:0xf bank_mask:0xf
	v_fmac_f32_dpp v29, v29, v28 row_shr:1 row_mask:0xf bank_mask:0xf
	v_fmac_f32_dpp v15, v15, v14 row_shr:1 row_mask:0xf bank_mask:0xf
	v_fmac_f32_dpp v17, v17, v16 row_shr:1 row_mask:0xf bank_mask:0xf
	v_mul_f32_dpp v26, v26, v26 row_shr:1 row_mask:0xf bank_mask:0xf
	v_mul_f32_dpp v28, v28, v28 row_shr:1 row_mask:0xf bank_mask:0xf
	v_mul_f32_dpp v14, v14, v14 row_shr:1 row_mask:0xf bank_mask:0xf
	v_mul_f32_dpp v16, v16, v16 row_shr:1 row_mask:0xf bank_mask:0xf
	v_fmac_f32_dpp v27, v27, v26 row_shr:2 row_mask:0xf bank_mask:0xf
	v_fmac_f32_dpp v29, v29, v28 row_shr:2 row_mask:0xf bank_mask:0xf
	v_fmac_f32_dpp v15, v15, v14 row_shr:2 row_mask:0xf bank_mask:0xf
	v_fmac_f32_dpp v17, v17, v16 row_shr:2 row_mask:0xf bank_mask:0xf
	v_mul_f32_dpp v26, v26, v26 row_shr:2 row_mask:0xf bank_mask:0xf
	v_mul_f32_dpp v28, v28, v28 row_shr:2 row_mask:0xf bank_mask:0xf
	v_mul_f32_dpp v14, v14, v14 row_shr:2 row_mask:0xf bank_mask:0xf
	v_mul_f32_dpp v16, v16, v16 row_shr:2 row_mask:0xf bank_mask:0xf
	v_fmac_f32_dpp v27, v27, v26 row_shr:4 row_mask:0xf bank_mask:0xf
	v_fmac_f32_dpp v29, v29, v28 row_shr:4 row_mask:0xf bank_mask:0xf
	v_fmac_f32_dpp v15, v15, v14 row_shr:4 row_mask:0xf bank_mask:0xf
	v_fmac_f32_dpp v17, v17, v16 row_shr:4 row_mask:0xf bank_mask:0xf
	v_mul_f32_dpp v26, v26, v26 row_shr:4 row_mask:0xf bank_mask:0xf
	v_mul_f32_dpp v28, v28, v28 row_shr:4 row_mask:0xf bank_mask:0xf
	v_mul_f32_dpp v14, v14, v14 row_shr:4 row_mask:0xf bank_mask:0xf
	v_mul_f32_dpp v16, v16, v16 row_shr:4 row_mask:0xf bank_mask:0xf
	v_fmac_f32_dpp v27, v27, v26 row_shr:8 row_mask:0xf bank_mask:0xf
	v_fmac_f32_dpp v29, v29, v28 row_shr:8 row_mask:0xf bank_mask:0xf
	v_fmac_f32_dpp v15, v15, v14 row_shr:8 row_mask:0xf bank_mask:0xf
	v_fmac_f32_dpp v17, v17, v16 row_shr:8 row_mask:0xf bank_mask:0xf
	v_mul_f32_dpp v26, v26, v26 row_shr:8 row_mask:0xf bank_mask:0xf
	v_mul_f32_dpp v28, v28, v28 row_shr:8 row_mask:0xf bank_mask:0xf
	v_mul_f32_dpp v14, v14, v14 row_shr:8 row_mask:0xf bank_mask:0xf
	v_mul_f32_dpp v16, v16, v16 row_shr:8 row_mask:0xf bank_mask:0xf
	v_fmac_f32_dpp v27, v27, v26 row_bcast:15 row_mask:0xa bank_mask:0xf
	v_fmac_f32_dpp v29, v29, v28 row_bcast:15 row_mask:0xa bank_mask:0xf
	v_fmac_f32_dpp v15, v15, v14 row_bcast:15 row_mask:0xa bank_mask:0xf
	v_fmac_f32_dpp v17, v17, v16 row_bcast:15 row_mask:0xa bank_mask:0xf
	v_mul_f32_dpp v26, v26, v26 row_bcast:15 row_mask:0xa bank_mask:0xf
	v_mul_f32_dpp v28, v28, v28 row_bcast:15 row_mask:0xa bank_mask:0xf
	v_mul_f32_dpp v14, v14, v14 row_bcast:15 row_mask:0xa bank_mask:0xf
	v_mul_f32_dpp v16, v16, v16 row_bcast:15 row_mask:0xa bank_mask:0xf

; __device__ __forceinline__ unsigned cvt_pk_bf16(float lo, float hi) { unsigned r; asm volatile("v_cvt_pk_bf16_f32 %0, %1, %2" : "=v"(r) : "v"(lo), "v"(hi)); return r; }
; template <int PASS>
; __device__ __forceinline__ void lru_unit(const LruPtrs& args, LAS unsigned char* lds, int chunk, int bl, int g, int ck) {
;     ...
;     for (int q = 0; q < 8; ++q) { v4u st;
; #pragma unroll
;         for (int p = 0; p < 4; ++p) st[p] = pg8::cvt_pk_bf16(av[q][p], uv[q][p]);
;         stash[q * 64] = st; }
;     }
;     ...
;     if (PASS == 1 && n == 31) {
; #pragma unroll
;         for (int q = 0; q < 8; ++q)
; #pragma unroll
;             for (int p = 0; p < 4; ++p) { const int ci = 8 * q + 4 * hi + p; WAG[(w * 64 + ci) * 2] = av[q][p]; WAG[(w * 64 + ci) * 2 + 1] = uv[q][p]; }
	s_nop 0
	v_cvt_pk_bf16_f32 v30, v66, v67
	v_cvt_pk_bf16_f32 v31, v68, v69
	v_cvt_pk_bf16_f32 v32, v34, v35
	v_cvt_pk_bf16_f32 v33, v36, v37
	s_nop 0
	v_addc_co_u32_e32 v73, vcc, 0, v73, vcc
	global_store_dwordx4 v[72:73], v[30:33], off offset:-4096 nt
	v_cmp_eq_u32_e32 vcc, 31, v87
	s_nop 0
	v_cvt_pk_bf16_f32 v30, v50, v51
	v_cvt_pk_bf16_f32 v31, v52, v53
	v_cvt_pk_bf16_f32 v32, v38, v39
	v_cvt_pk_bf16_f32 v33, v40, v41
	global_store_dwordx4 v[70:71], v[30:33], off offset:1024 nt
	s_nop 1
	v_cvt_pk_bf16_f32 v30, v54, v55
	v_cvt_pk_bf16_f32 v31, v56, v57
	v_cvt_pk_bf16_f32 v32, v42, v43
	v_cvt_pk_bf16_f32 v33, v44, v45
	global_store_dwordx4 v[70:71], v[30:33], off offset:2048 nt
	s_nop 1
	v_cvt_pk_bf16_f32 v30, v58, v59
	v_cvt_pk_bf16_f32 v31, v60, v61
	v_cvt_pk_bf16_f32 v32, v46, v47
	v_cvt_pk_bf16_f32 v33, v48, v49
	global_store_dwordx4 v[70:71], v[30:33], off offset:3072 nt
	s_nop 1
	v_cvt_pk_bf16_f32 v30, v62, v63
	v_cvt_pk_bf16_f32 v31, v64, v65
	v_cvt_pk_bf16_f32 v32, v2, v3
	v_cvt_pk_bf16_f32 v33, v4, v5
	global_store_dwordx4 v[72:73], v[30:33], off nt
	s_nop 1
	v_cvt_pk_bf16_f32 v30, v18, v19
	v_cvt_pk_bf16_f32 v31, v20, v21
	v_cvt_pk_bf16_f32 v32, v6, v7
	v_cvt_pk_bf16_f32 v33, v8, v9
	global_store_dwordx4 v[72:73], v[30:33], off offset:1024 nt
	s_nop 1
	v_cvt_pk_bf16_f32 v30, v22, v23
	v_cvt_pk_bf16_f32 v31, v24, v25
	v_cvt_pk_bf16_f32 v32, v10, v11
	v_cvt_pk_bf16_f32 v33, v12, v13
	global_store_dwordx4 v[72:73], v[30:33], off offset:2048 nt
	s_nop 1
	v_cvt_pk_bf16_f32 v30, v26, v27
	v_cvt_pk_bf16_f32 v31, v28, v29
	v_cvt_pk_bf16_f32 v32, v14, v15
	v_cvt_pk_bf16_f32 v33, v16, v17
	global_store_dwordx4 v[72:73], v[30:33], off offset:3072 nt
	s_and_saveexec_b64 s[4:5], vcc
	s_cbranch_execz .LBB0_447
	v_or_b32_e32 v0, s47, v88
	v_lshl_add_u32 v0, v0, 3, 0
	ds_write_b128 v0, v[66:69]
	ds_write_b128 v0, v[34:37] offset:16
	ds_write_b128 v0, v[50:53] offset:64
	ds_write_b128 v0, v[38:41] offset:80
	ds_write_b128 v0, v[54:57] offset:128
	ds_write_b128 v0, v[42:45] offset:144
	ds_write_b128 v0, v[58:61] offset:192
	ds_write_b128 v0, v[46:49] offset:208
	ds_write_b128 v0, v[62:65] offset:256
	ds_write_b128 v0, v[2:5] offset:272
	ds_write_b128 v0, v[18:21] offset:320
	ds_write_b128 v0, v[6:9] offset:336
	ds_write_b128 v0, v[22:25] offset:384
	ds_write_b128 v0, v[10:13] offset:400
	ds_write_b128 v0, v[26:29] offset:448
	ds_write_b128 v0, v[14:17] offset:464
